# GLA-G3 att stage: K fragments read up front and the triangular mask applied by one sign test per element
# baseline (speedup 1.0000x reference)
; #define LAS __attribute__((address_space(3)))
; __device__ __forceinline__ bf16_t f2bf(float f) { unsigned u = __float_as_uint(f); u += 0x7FFFu + ((u >> 16) & 1u); return (bf16_t)(u >> 16); }
; __device__ __forceinline__ f32x4 mfma16(bf16x8 a, bf16x8 b, f32x4 c) { return __builtin_amdgcn_mfma_f32_16x16x32_bf16(a, b, c, 0, 0, 0); }
; __device__ __forceinline__ void gla_g3_item(int wv, const Params& p, int l, int b, int n, int h, LAS unsigned char* lds) {
;     ...
;     { const int dir = wave >> 2, mi = wave & 3;
;       bf16x8 a[2];
; #pragma unroll
;       for (int kk = 0; kk < 2; ++kk) a[kk] = *(const LAS bf16x8*)(lds + GL_Q + (dir * 64 + mi * 16 + fr) * 144 + kk * 64 + fq * 16);
; #pragma unroll
;       for (int ni = 0; ni < 4; ++ni) { f32x4 acc = (f32x4){0.f, 0.f, 0.f, 0.f};
; #pragma unroll
;           for (int kk = 0; kk < 2; ++kk) { const bf16x8 bb = *(const LAS bf16x8*)(lds + GL_K + (dir * 64 + ni * 16 + fr) * 144 + kk * 64 + fq * 16); acc = mfma16(a[kk], bb, acc); }
; #pragma unroll
;           for (int i = 0; i < 4; ++i) { const int t = mi * 16 + fq * 4 + i, sidx = ni * 16 + fr; const bool keep = dir ? (sidx >= t) : (sidx <= t);
;               *(LAS bf16_t*)(lds + GL_X + (dir * 64 + t) * 144 + sidx * 2) = f2bf(keep ? acc[i] : 0.f); } } }
.LBB0_954:
	s_or_b64 exec, exec, s[4:5]
	v_ashrrev_i32_e32 v3, 2, v2
	v_and_b32_e32 v3, 0xffffffc0, v3
	v_lshlrev_b32_e32 v4, 4, v82
	v_and_b32_e32 v26, 48, v4
	v_or_b32_e32 v4, v3, v81
	v_or_b32_e32 v5, v4, v26
	v_mul_lo_u32 v5, v5, s55
	v_add3_u32 v18, 0, v5, v0
	s_waitcnt lgkmcnt(0)
	s_barrier
	ds_read_b128 v[10:13], v18 offset:39424
	v_mad_u64_u32 v[4:5], s[4:5], v4, s55, v[38:39]
	ds_read_b128 v[18:21], v18 offset:39488
	ds_read_b128 v[112:115], v4 offset:57856
	ds_read_b128 v[116:119], v4 offset:57920
	ds_read_b128 v[120:123], v4 offset:60160
	ds_read_b128 v[124:127], v4 offset:60224
	ds_read_b128 v[132:135], v4 offset:62464
	ds_read_b128 v[136:139], v4 offset:62528
	ds_read_b128 v[140:143], v4 offset:64768
	ds_read_b128 v[144:147], v4 offset:64832
	v_cmp_gt_u32_e32 vcc, s43, v2
	v_and_b32_e32 v2, 64, v2
	v_or_b32_e32 v5, v26, v40
	v_sub_u32_e32 v22, v5, v81
	v_sub_u32_e32 v23, v81, v5
	v_cndmask_b32_e64 v27, 16, -16, vcc
	v_cndmask_b32_e64 v24, -1, 1, vcc
	v_cndmask_b32_e32 v164, v23, v22, vcc
	v_add_u32_e32 v165, v164, v24
	v_add_u32_e32 v166, v165, v24
	v_add_u32_e32 v167, v166, v24
	v_or_b32_e32 v29, v5, v3
	v_mul_lo_u32 v29, v29, s55
	s_add_i32 s3, 0, 0x16000
	v_lshl_add_u32 v22, v81, 1, s3
	v_add_u32_e32 v29, v29, v22
	v_add_u32_e32 v33, s87, v0
	v_mov_b32_e32 v61, v1
	s_mov_b64 s[4:5], 0x800500
	v_and_b32_e32 v32, -16, v63
	s_add_u32 s14, s30, s8
	s_addc_u32 s15, s31, s9
	s_waitcnt lgkmcnt(4)
	v_mfma_f32_16x16x32_bf16 v[148:151], v[10:13], v[112:115], 0
	v_mfma_f32_16x16x32_bf16 v[152:155], v[10:13], v[120:123], 0
	v_mfma_f32_16x16x32_bf16 v[148:151], v[18:21], v[116:119], v[148:151]
	v_mfma_f32_16x16x32_bf16 v[152:155], v[18:21], v[124:127], v[152:155]
	s_waitcnt lgkmcnt(0)
	v_mfma_f32_16x16x32_bf16 v[156:159], v[10:13], v[132:135], 0
	v_mfma_f32_16x16x32_bf16 v[160:163], v[10:13], v[140:143], 0
	v_mfma_f32_16x16x32_bf16 v[156:159], v[18:21], v[136:139], v[156:159]
	v_mfma_f32_16x16x32_bf16 v[160:163], v[18:21], v[144:147], v[160:163]
	v_ashrrev_i32_e32 v23, 31, v164
	v_bfi_b32 v24, v23, 0, v148
	v_bfe_u32 v23, v24, 16, 1
	v_add3_u32 v24, v24, v23, s54
	ds_write_b16_d16_hi v29, v24
	v_ashrrev_i32_e32 v25, 31, v165
	v_bfi_b32 v28, v25, 0, v149
	v_bfe_u32 v25, v28, 16, 1
	v_add3_u32 v28, v28, v25, s54
	ds_write_b16_d16_hi v29, v28 offset:144
	v_ashrrev_i32_e32 v23, 31, v166
	v_bfi_b32 v24, v23, 0, v150
	v_bfe_u32 v23, v24, 16, 1
	v_add3_u32 v24, v24, v23, s54
	ds_write_b16_d16_hi v29, v24 offset:288
	v_ashrrev_i32_e32 v25, 31, v167
	v_bfi_b32 v28, v25, 0, v151
	v_bfe_u32 v25, v28, 16, 1
	v_add3_u32 v28, v28, v25, s54
	ds_write_b16_d16_hi v29, v28 offset:432
	v_add_u32_e32 v164, v164, v27
	v_add_u32_e32 v165, v165, v27
	v_add_u32_e32 v166, v166, v27
	v_add_u32_e32 v167, v167, v27
	v_ashrrev_i32_e32 v23, 31, v164
	v_bfi_b32 v24, v23, 0, v152
	v_bfe_u32 v23, v24, 16, 1
	v_add3_u32 v24, v24, v23, s54
	ds_write_b16_d16_hi v29, v24 offset:32
	v_ashrrev_i32_e32 v25, 31, v165
	v_bfi_b32 v28, v25, 0, v153
	v_bfe_u32 v25, v28, 16, 1
	v_add3_u32 v28, v28, v25, s54
	ds_write_b16_d16_hi v29, v28 offset:176
	v_ashrrev_i32_e32 v23, 31, v166
	v_bfi_b32 v24, v23, 0, v154
	v_bfe_u32 v23, v24, 16, 1
	v_add3_u32 v24, v24, v23, s54
	ds_write_b16_d16_hi v29, v24 offset:320
	v_ashrrev_i32_e32 v25, 31, v167
	v_bfi_b32 v28, v25, 0, v155
	v_bfe_u32 v25, v28, 16, 1
	v_add3_u32 v28, v28, v25, s54
	ds_write_b16_d16_hi v29, v28 offset:464
	v_add_u32_e32 v164, v164, v27
	v_add_u32_e32 v165, v165, v27
	v_add_u32_e32 v166, v166, v27
	v_add_u32_e32 v167, v167, v27
	v_ashrrev_i32_e32 v23, 31, v164
	v_bfi_b32 v24, v23, 0, v156
	v_bfe_u32 v23, v24, 16, 1
	v_add3_u32 v24, v24, v23, s54
	ds_write_b16_d16_hi v29, v24 offset:64
	v_ashrrev_i32_e32 v25, 31, v165
	v_bfi_b32 v28, v25, 0, v157
	v_bfe_u32 v25, v28, 16, 1
	v_add3_u32 v28, v28, v25, s54
	ds_write_b16_d16_hi v29, v28 offset:208
	v_ashrrev_i32_e32 v23, 31, v166
	v_bfi_b32 v24, v23, 0, v158
	v_bfe_u32 v23, v24, 16, 1
	v_add3_u32 v24, v24, v23, s54
	ds_write_b16_d16_hi v29, v24 offset:352
	v_ashrrev_i32_e32 v25, 31, v167
	v_bfi_b32 v28, v25, 0, v159
	v_bfe_u32 v25, v28, 16, 1
	v_add3_u32 v28, v28, v25, s54
	ds_write_b16_d16_hi v29, v28 offset:496
	v_add_u32_e32 v164, v164, v27
	v_add_u32_e32 v165, v165, v27
	v_add_u32_e32 v166, v166, v27
	v_add_u32_e32 v167, v167, v27
	v_ashrrev_i32_e32 v23, 31, v164
	v_bfi_b32 v24, v23, 0, v160
	v_bfe_u32 v23, v24, 16, 1
	v_add3_u32 v24, v24, v23, s54
	ds_write_b16_d16_hi v29, v24 offset:96
	v_ashrrev_i32_e32 v25, 31, v165
	v_bfi_b32 v28, v25, 0, v161
	v_bfe_u32 v25, v28, 16, 1
	v_add3_u32 v28, v28, v25, s54
	ds_write_b16_d16_hi v29, v28 offset:240
	v_ashrrev_i32_e32 v23, 31, v166
	v_bfi_b32 v24, v23, 0, v162
	v_bfe_u32 v23, v24, 16, 1
	v_add3_u32 v24, v24, v23, s54
	ds_write_b16_d16_hi v29, v24 offset:384
	v_ashrrev_i32_e32 v25, 31, v167
	v_bfi_b32 v28, v25, 0, v163
	v_bfe_u32 v25, v28, 16, 1
	v_add3_u32 v28, v28, v25, s54
	ds_write_b16_d16_hi v29, v28 offset:528
	v_cmp_ne_u32_e32 vcc, 0, v2
	v_or_b32_e32 v2, v32, v81
	v_mul_lo_u32 v14, v2, s55
	v_add3_u32 v34, s3, v0, v14
	s_waitcnt lgkmcnt(0)
	s_barrier
; #define LAS __attribute__((address_space(3)))
; __device__ __forceinline__ f32x4 mfma16(bf16x8 a, bf16x8 b, f32x4 c) { return __builtin_amdgcn_mfma_f32_16x16x32_bf16(a, b, c, 0, 0, 0); }
; __device__ __forceinline__ void gla_g3_item(int wv, const Params& p, int l, int b, int n, int h, LAS unsigned char* lds) {
;     ...
;     { const int mi = wave >> 1, nb = (wave & 1) * 3;
; #pragma unroll
;       for (int nn = 0; nn < 3; ++nn) { const int ni = nb + nn; f32x4 acc = (f32x4){0.f, 0.f, 0.f, 0.f};
; #pragma unroll
;           for (int dir = 0; dir < 2; ++dir)
; #pragma unroll
;               for (int kk = 0; kk < 2; ++kk) {
;                   const bf16x8 a1 = *(const LAS bf16x8*)(lds + GL_X + (dir * 64 + mi * 16 + fr) * 144 + kk * 64 + fq * 16);
;                   const bf16x8 b1 = *(const LAS bf16x8*)(lds + GL_VT + (ni * 16 + fr) * 144 + kk * 64 + fq * 16);
;                   acc = mfma16(a1, b1, acc);
;                   const bf16x8 a2 = *(const LAS bf16x8*)(lds + GL_Q + (dir * 64 + mi * 16 + fr) * 144 + kk * 64 + fq * 16);
;                   const bf16x8 b2 = *(const LAS bf16x8*)(lds + GL_ST + (dir * 96 + ni * 16 + fr) * 144 + kk * 64 + fq * 16);
;                   acc = mfma16(a2, b2, acc); }
; #pragma unroll
;           for (int i = 0; i < 4; ++i) Ob[(mi * 16 + fq * 4 + i) * 97 + ni * 16 + fr] = acc[i]; } }
	ds_read_b128 v[20:23], v34
	v_cndmask_b32_e64 v31, 0, 3, vcc
	v_lshl_or_b32 v29, v31, 4, v81
	v_mad_u32_u24 v15, v29, s55, v33
	v_add_u32_e32 v35, v38, v14
	v_add_u32_e32 v0, s70, v0
	v_mad_u32_u24 v36, v29, s55, v0
	ds_read_b128 v[112:115], v15
	ds_read_b128 v[116:119], v15 offset:2304
	ds_read_b128 v[120:123], v15 offset:4608
	ds_read_b128 v[24:27], v35 offset:39424
	ds_read_b128 v[124:127], v36
	ds_read_b128 v[132:135], v36 offset:2304
	ds_read_b128 v[136:139], v36 offset:4608
	v_or_b32_e32 v29, v32, v40
	v_mul_lo_u32 v32, v29, s64
	v_lshlrev_b32_e32 v37, 6, v31
	v_add3_u32 v37, v39, v37, v32
	s_waitcnt lgkmcnt(4)
	v_mfma_f32_16x16x32_bf16 v[2:5], v[20:23], v[112:115], 0
	v_mfma_f32_16x16x32_bf16 v[10:13], v[20:23], v[116:119], 0
	v_mfma_f32_16x16x32_bf16 v[16:19], v[20:23], v[120:123], 0
	ds_read_b128 v[20:23], v34 offset:64
	ds_read_b128 v[112:115], v15 offset:64
	ds_read_b128 v[116:119], v15 offset:2368
	ds_read_b128 v[120:123], v15 offset:4672
	s_waitcnt lgkmcnt(4)
	v_mfma_f32_16x16x32_bf16 v[2:5], v[24:27], v[124:127], v[2:5]
	v_mfma_f32_16x16x32_bf16 v[10:13], v[24:27], v[132:135], v[10:13]
	v_mfma_f32_16x16x32_bf16 v[16:19], v[24:27], v[136:139], v[16:19]
	ds_read_b128 v[24:27], v35 offset:39488
	ds_read_b128 v[124:127], v36 offset:64
	ds_read_b128 v[132:135], v36 offset:2368
	ds_read_b128 v[136:139], v36 offset:4672
	s_waitcnt lgkmcnt(4)
	v_mfma_f32_16x16x32_bf16 v[2:5], v[20:23], v[112:115], v[2:5]
	v_mfma_f32_16x16x32_bf16 v[10:13], v[20:23], v[116:119], v[10:13]
	v_mfma_f32_16x16x32_bf16 v[16:19], v[20:23], v[120:123], v[16:19]
	ds_read_b128 v[20:23], v34 offset:9216
	ds_read_b128 v[112:115], v15
	ds_read_b128 v[116:119], v15 offset:2304
	ds_read_b128 v[120:123], v15 offset:4608
	s_waitcnt lgkmcnt(4)
	v_mfma_f32_16x16x32_bf16 v[2:5], v[24:27], v[124:127], v[2:5]
	v_mfma_f32_16x16x32_bf16 v[10:13], v[24:27], v[132:135], v[10:13]
	v_mfma_f32_16x16x32_bf16 v[16:19], v[24:27], v[136:139], v[16:19]
	ds_read_b128 v[24:27], v35 offset:48640
	ds_read_b128 v[124:127], v36 offset:13824
	ds_read_b128 v[132:135], v36 offset:16128
	ds_read_b128 v[136:139], v36 offset:18432
	s_waitcnt lgkmcnt(4)
	v_mfma_f32_16x16x32_bf16 v[2:5], v[20:23], v[112:115], v[2:5]
	v_mfma_f32_16x16x32_bf16 v[10:13], v[20:23], v[116:119], v[10:13]
	v_mfma_f32_16x16x32_bf16 v[16:19], v[20:23], v[120:123], v[16:19]
	ds_read_b128 v[20:23], v34 offset:9280
	ds_read_b128 v[112:115], v15 offset:64
	ds_read_b128 v[116:119], v15 offset:2368
	ds_read_b128 v[120:123], v15 offset:4672
	s_waitcnt lgkmcnt(4)
	v_mfma_f32_16x16x32_bf16 v[2:5], v[24:27], v[124:127], v[2:5]
	v_mfma_f32_16x16x32_bf16 v[10:13], v[24:27], v[132:135], v[10:13]
	v_mfma_f32_16x16x32_bf16 v[16:19], v[24:27], v[136:139], v[16:19]
	ds_read_b128 v[24:27], v35 offset:48704
	ds_read_b128 v[124:127], v36 offset:13888
	ds_read_b128 v[132:135], v36 offset:16192
	ds_read_b128 v[136:139], v36 offset:18496
	s_waitcnt lgkmcnt(4)
	v_mfma_f32_16x16x32_bf16 v[2:5], v[20:23], v[112:115], v[2:5]
	v_mfma_f32_16x16x32_bf16 v[10:13], v[20:23], v[116:119], v[10:13]
	v_mfma_f32_16x16x32_bf16 v[16:19], v[20:23], v[120:123], v[16:19]
	s_waitcnt lgkmcnt(0)
	v_mfma_f32_16x16x32_bf16 v[2:5], v[24:27], v[124:127], v[2:5]
	v_mfma_f32_16x16x32_bf16 v[10:13], v[24:27], v[132:135], v[10:13]
	v_mfma_f32_16x16x32_bf16 v[16:19], v[24:27], v[136:139], v[16:19]
	s_nop 7
	v_add_u32_e32 v29, 0x200, v37
	ds_write2_b32 v37, v2, v3 offset1:97
	ds_write2_b32 v29, v4, v5 offset0:66 offset1:163
	ds_write2_b32 v37, v10, v11 offset0:16 offset1:113
	ds_write2_b32 v29, v12, v13 offset0:82 offset1:179
	ds_write2_b32 v37, v16, v17 offset0:32 offset1:129
	ds_write2_b32 v29, v18, v19 offset0:98 offset1:195
	s_waitcnt vmcnt(0)
	v_lshlrev_b32_e32 v26, 16, v7
	v_and_b32_e32 v28, 0xffff0000, v7
	v_mul_lo_u32 v10, v63, s64
	v_lshlrev_b32_e32 v0, 2, v65
	s_waitcnt lgkmcnt(0)
	s_barrier
; __device__ __forceinline__ unsigned pk_bf16(float lo, float hi) { unsigned r; asm volatile("v_cvt_pk_bf16_f32 %0, %1, %2" : "=v"(r) : "v"(lo), "v"(hi)); return r; }
; __device__ __forceinline__ float bflo(unsigned w) { return __uint_as_float(w << 16); }
; __device__ __forceinline__ float bfhi(unsigned w) { return __uint_as_float(w & 0xffff0000u); }
; __device__ __forceinline__ float shx(float v, int m, int lane) { return __int_as_float(__builtin_amdgcn_ds_bpermute((lane ^ m) << 2, __float_as_int(v))); }
; __device__ __forceinline__ void gla_g3_item(int wv, const Params& p, int l, int b, int n, int h, LAS unsigned char* lds) {
;     ...
;     { const int t = tf; float o[12]; float ss = 0.f;
; #pragma unroll
;       for (int e = 0; e < 12; ++e) { o[e] = Ob[t * 97 + part * 12 + e]; ss += o[e] * o[e]; }
;       ss += shx(ss, 1, lane); ss += shx(ss, 2, lane); ss += shx(ss, 4, lane);
;       const float rs = rsqrtf(ss * (1.0f / 96.0f) + 1e-6f);
;       const float* gn = p.gla_o_norm + l * 96 + part * 12;
;       bf16_t* yp = (bf16_t*)(p.ws + OFF_HY) + (size_t)(row0 + t) * 1024 + 640 + h * 96 + part * 12;
; #pragma unroll
;       for (int q4 = 0; q4 < 3; ++q4) { const u32x2 gw = ggw[q4]; float g[4] = {bflo(gw.x), bfhi(gw.x), bflo(gw.y), bfhi(gw.y)}; float r[4];
; #pragma unroll
;           for (int e = 0; e < 4; ++e) r[e] = o[q4 * 4 + e] * rs * gn[q4 * 4 + e] * (g[e] * __builtin_amdgcn_rcpf(1.f + __expf(-g[e])));
;           u32x2 w; w.x = pk_bf16(r[0], r[1]); w.y = pk_bf16(r[2], r[3]); *(u32x2*)(yp + q4 * 4) = w; } }
	global_load_dwordx4 v[2:5], v0, s[14:15]
	global_load_dwordx4 v[144:147], v0, s[14:15] offset:16
	global_load_dwordx4 v[148:151], v0, s[14:15] offset:32
	v_add3_u32 v22, 0, v10, v0
	ds_read2_b32 v[10:11], v22 offset1:1
	ds_read2_b32 v[12:13], v22 offset0:2 offset1:3
	ds_read2_b32 v[14:15], v22 offset0:4 offset1:5
	ds_read2_b32 v[16:17], v22 offset0:6 offset1:7
	s_waitcnt lgkmcnt(3)
	v_mul_f32_e32 v20, v11, v11
	v_fmac_f32_e32 v20, v10, v10
	s_waitcnt lgkmcnt(2)
	v_fmac_f32_e32 v20, v12, v12
	v_fmac_f32_e32 v20, v13, v13
	s_waitcnt lgkmcnt(1)
	v_pk_mul_f32 v[18:19], v[14:15], v[14:15]
	s_waitcnt vmcnt(0)
	v_mov_b32_e32 v31, v2
	v_add_f32_e32 v18, v20, v18
	v_add_f32_e32 v23, v18, v19
	ds_read2_b32 v[18:19], v22 offset0:8 offset1:9
	s_waitcnt lgkmcnt(1)
	v_pk_mul_f32 v[20:21], v[16:17], v[16:17]
	s_nop 0
	v_add_f32_e32 v20, v23, v20
	ds_read2_b32 v[22:23], v22 offset0:10 offset1:11
	v_add_f32_e32 v24, v20, v21
	s_waitcnt lgkmcnt(1)
	v_pk_mul_f32 v[20:21], v[18:19], v[18:19]
	s_nop 0
	v_add_f32_e32 v20, v24, v20
	v_add_f32_e32 v24, v20, v21
	s_waitcnt lgkmcnt(0)
	v_pk_mul_f32 v[20:21], v[22:23], v[22:23]
	s_nop 0
	v_add_f32_e32 v20, v24, v20
	v_add_f32_e32 v20, v20, v21
	v_lshlrev_b32_e32 v21, 2, v30
	v_xor_b32_e32 v24, 4, v21
	s_nop 1
	v_mov_b32_dpp v24, v20 quad_perm:[1,0,3,2] row_mask:0xf bank_mask:0xf
	s_waitcnt lgkmcnt(0)
	v_add_f32_e32 v20, v20, v24
	v_xor_b32_e32 v24, 8, v21
	s_nop 1
	v_mov_b32_dpp v24, v20 quad_perm:[2,3,0,1] row_mask:0xf bank_mask:0xf
	v_xor_b32_e32 v21, 16, v21
	s_waitcnt lgkmcnt(0)
	v_add_f32_e32 v20, v20, v24
	s_nop 1
	v_mov_b32_dpp v21, v20 row_half_mirror row_mask:0xf bank_mask:0xf
	v_lshlrev_b32_e32 v24, 16, v6
	v_and_b32_e32 v6, 0xffff0000, v6
	v_mul_f32_e32 v7, 0xbfb8aa3b, v24
	v_exp_f32_e32 v7, v7
	s_waitcnt lgkmcnt(0)
	v_add_f32_e32 v20, v20, v21
	v_fmamk_f32 v20, v20, 0x3c2aaaab, v197
	v_mul_f32_e32 v21, 0x4b800000, v20
	v_cmp_gt_f32_e32 vcc, s68, v20
	v_add_f32_e32 v7, 1.0, v7
	v_rcp_f32_e32 v30, v7
	v_cndmask_b32_e32 v20, v20, v21, vcc
	v_rsq_f32_e32 v20, v20
	s_nop 0
	v_mul_f32_e32 v21, 0x45800000, v20
	v_cndmask_b32_e32 v32, v20, v21, vcc
	v_mul_f32_e32 v25, v10, v32
	v_mul_f32_e32 v10, 0xbfb8aa3b, v6
	v_exp_f32_e32 v10, v10
	v_mul_f32_e32 v7, v11, v32
	v_lshlrev_b64 v[20:21], 11, v[58:59]
	v_lshl_add_u64 v[20:21], s[6:7], 0, v[20:21]
	v_add_f32_e32 v2, 1.0, v10
	v_rcp_f32_e32 v2, v2
	v_lshl_add_u64 v[20:21], v[20:21], 0, s[56:57]
	v_mul_f32_e32 v27, v12, v32
	v_lshl_add_u64 v[20:21], v[20:21], 0, v[60:61]
	v_pk_mul_f32 v[2:3], v[2:3], v[6:7]
	v_mul_f32_e32 v29, v13, v32
	v_mul_f32_e32 v6, v2, v3
	v_mul_f32_e32 v2, 0xbfb8aa3b, v26
	v_exp_f32_e32 v2, v2
	v_mul_f32_e32 v3, 0xbfb8aa3b, v28
	v_exp_f32_e32 v7, v3
	v_mov_b32_e32 v3, v4
	v_add_f32_e32 v2, 1.0, v2
	v_rcp_f32_e32 v2, v2
	v_add_f32_e32 v4, 1.0, v7
	v_rcp_f32_e32 v4, v4
	v_pk_mul_f32 v[24:25], v[30:31], v[24:25]
	v_pk_mul_f32 v[2:3], v[2:3], v[26:27]
	v_mul_f32_e32 v10, v24, v25
	v_mul_f32_e32 v7, v2, v3
	v_pk_mul_f32 v[2:3], v[4:5], v[28:29]
	v_add_co_u32_e32 v4, vcc, s68, v20
	v_mul_f32_e32 v3, v2, v3
	s_nop 0
	v_addc_co_u32_e32 v5, vcc, 0, v21, vcc
	v_cvt_pk_bf16_f32 v2, v10, v6
	v_cvt_pk_bf16_f32 v3, v7, v3
	global_store_dwordx2 v[4:5], v[2:3], off offset:1280
	v_lshlrev_b32_e32 v10, 16, v8
	v_mul_f32_e32 v11, 0xbfb8aa3b, v10
	v_exp_f32_e32 v13, v11
	v_lshl_add_u64 v[6:7], v[20:21], 0, s[4:5]
	v_and_b32_e32 v8, 0xffff0000, v8
	v_lshlrev_b32_e32 v12, 16, v9
	v_and_b32_e32 v20, 0xffff0000, v9
	v_add_f32_e32 v9, 1.0, v13
	v_rcp_f32_e32 v24, v9
	v_mul_f32_e32 v9, 0xbfb8aa3b, v8
	v_exp_f32_e32 v9, v9
	v_mul_f32_e32 v11, v14, v32
	v_mov_b32_e32 v2, v144
	v_mov_b32_e32 v3, v145
	v_mov_b32_e32 v4, v146
	v_mov_b32_e32 v5, v147
	v_mov_b32_e32 v25, v2
	v_add_f32_e32 v2, 1.0, v9
	v_rcp_f32_e32 v2, v2
	v_pk_mul_f32 v[10:11], v[24:25], v[10:11]
	v_mul_f32_e32 v9, 0xbfb8aa3b, v12
	v_mul_f32_e32 v10, v10, v11
	v_exp_f32_e32 v11, v9
	v_mul_f32_e32 v9, v15, v32
	v_pk_mul_f32 v[2:3], v[2:3], v[8:9]
	v_mov_b32_e32 v13, v4
	v_mul_f32_e32 v14, v2, v3
	v_mul_f32_e32 v3, 0xbfb8aa3b, v20
	v_exp_f32_e32 v8, v3
	v_add_f32_e32 v2, 1.0, v11
	v_rcp_f32_e32 v2, v2
	v_mul_f32_e32 v3, v16, v32
	v_add_f32_e32 v4, 1.0, v8
	v_rcp_f32_e32 v8, v4
	v_pk_mul_f32 v[2:3], v[2:3], v[12:13]
	v_mul_f32_e32 v9, v17, v32
	v_mov_b32_e32 v21, v5
	v_mul_f32_e32 v4, v2, v3
	v_pk_mul_f32 v[2:3], v[8:9], v[20:21]
	v_lshlrev_b32_e32 v8, 16, v46
	v_mul_f32_e32 v3, v2, v3
	v_cvt_pk_bf16_f32 v2, v10, v14
	v_cvt_pk_bf16_f32 v3, v4, v3
	global_store_dwordx2 v[6:7], v[2:3], off offset:8
	v_mul_f32_e32 v0, 0xbfb8aa3b, v8
	v_exp_f32_e32 v0, v0
	v_and_b32_e32 v10, 0xffff0000, v46
	v_mul_f32_e32 v17, v18, v32
	v_lshlrev_b32_e32 v12, 16, v47
	v_add_f32_e32 v0, 1.0, v0
	v_rcp_f32_e32 v16, v0
	v_mul_f32_e32 v0, 0xbfb8aa3b, v10
	v_exp_f32_e32 v0, v0
	v_and_b32_e32 v14, 0xffff0000, v47
	v_add_f32_e32 v0, 1.0, v0
	v_mov_b32_e32 v2, v148
	v_mov_b32_e32 v3, v149
	v_mov_b32_e32 v4, v150
	v_mov_b32_e32 v5, v151
	v_mov_b32_e32 v9, v2
	v_pk_mul_f32 v[8:9], v[16:17], v[8:9]
	v_mov_b32_e32 v11, v3
	v_mul_f32_e32 v16, v8, v9
	v_rcp_f32_e32 v8, v0
	v_mul_f32_e32 v0, 0xbfb8aa3b, v12
	v_exp_f32_e32 v0, v0
	v_mul_f32_e32 v9, v19, v32
	v_pk_mul_f32 v[2:3], v[8:9], v[10:11]
	v_mov_b32_e32 v13, v4
	v_add_f32_e32 v0, 1.0, v0
	v_mul_f32_e32 v10, v2, v3
	v_rcp_f32_e32 v2, v0
	v_mul_f32_e32 v0, 0xbfb8aa3b, v14
	v_exp_f32_e32 v0, v0
	v_mul_f32_e32 v3, v22, v32
	v_pk_mul_f32 v[2:3], v[2:3], v[12:13]
	v_mul_f32_e32 v9, v23, v32
	v_add_f32_e32 v0, 1.0, v0
	v_rcp_f32_e32 v8, v0
	v_mov_b32_e32 v15, v5
	v_mul_f32_e32 v0, v2, v3
	v_pk_mul_f32 v[2:3], v[8:9], v[14:15]
	s_nop 0
	v_mul_f32_e32 v3, v2, v3
	v_cvt_pk_bf16_f32 v2, v16, v10
	v_cvt_pk_bf16_f32 v3, v0, v3
	global_store_dwordx2 v[6:7], v[2:3], off offset:16
